# residual GEMM epilogues: a lane's two adjacent 8-byte bf16 stores paired into one 16-byte store (16 fewer store instructions per wave and unit)
# speedup vs baseline: 1.0104x; 1.0076x over previous
; __device__ __forceinline__ unsigned cvtpk(float lo, float hi) { f32x2 v = {lo, hi}; bf16x2_t b = __builtin_convertvector(v, bf16x2_t); return __builtin_bit_cast(unsigned, b); }
; #define SWZ_XOR(v, m) __uint_as_float((unsigned)__builtin_amdgcn_ds_swizzle((int)__float_as_uint(v), ((m) << 10) | 0x1f))
; __device__ __forceinline__ float sum32x(float v) { auto rr = __builtin_amdgcn_permlane32_swap(__float_as_uint(v), __float_as_uint(v), false, false); return __uint_as_float(rr[0]) + __uint_as_float(rr[1]); }
;     __device__ __forceinline__ void operator()(const pg8::f32x4 (&acc)[2][2][4][2], const pg8::Unit& u, int wr, int wc, int fr, int fq) const {
;     ...
;         } else if (kind == EK_RES) {
; #pragma unroll
;             for (int ai = 0; ai < 2; ++ai) {
;                 pg8::f32x4 pre[4][2][2];
; #pragma unroll
;                 for (int m = 0; m < 4; ++m) {
;                     const size_t ro = (size_t)(rowb + 128 * ai + 16 * m) * ldc + colb;
; #pragma unroll
;                     for (int bj = 0; bj < 2; ++bj)
; #pragma unroll
;                         for (int n = 0; n < 2; ++n) pre[m][bj][n] = *(const pg8::f32x4*)(fin + ro + 128 * bj + NS * n);
;                 }
; #pragma unroll
;                 for (int m = 0; m < 4; ++m) {
;                     const size_t ro = (size_t)(rowb + 128 * ai + 16 * m) * ldc + colb;
;                     float ssr = 0.f;
; #pragma unroll
;                     for (int bj = 0; bj < 2; ++bj)
; #pragma unroll
;                         for (int n = 0; n < 2; ++n) {
;                             const size_t off = ro + 128 * bj + NS * n;
;                             const pg8::f32x4 v = pre[m][bj][n] + acc[ai][bj][m][n] * coef;
;                             *(pg8::f32x4*)(fout + off) = v;
;                             if (flags & 2) { u32x2 w; w.x = cvtpk(v[0], v[1]); w.y = cvtpk(v[2], v[3]); *(u32x2*)(o0 + off) = w; ssr += (v[0] * v[0] + v[1] * v[1]) + (v[2] * v[2] + v[3] * v[3]); }
;                         }
;                     if (flags & 2) { ssr += SWZ_XOR(ssr, 16); ssr = sum32x(ssr); if (fq == 0) atomicAdd((float*)o1 + (rowb + 128 * ai + 16 * m), ssr); }
;                 }
.LBB0_1068:
	v_mov_b32_e32 v221, v216
	v_mov_b32_e32 v223, v218
	s_andn2_b64 vcc, exec, s[8:9]
	s_cbranch_vccnz .LBB0_1118
	v_ashrrev_i32_e32 v231, 31, v230
	v_or_b32_e32 v64, 16, v228
	v_lshl_add_u64 v[234:235], v[230:231], 2, v[136:137]
	v_mad_i64_i32 v[140:141], s[8:9], v65, v228, 0
	v_mad_i64_i32 v[240:241], s[8:9], v65, v64, 0
	v_or_b32_e32 v64, 32, v228
	v_lshl_add_u64 v[140:141], v[140:141], 2, v[234:235]
	v_mad_i64_i32 v[238:239], s[8:9], v65, v64, 0
	v_or_b32_e32 v64, 48, v228
	global_load_dword v66, v215, s[40:41] offset:1040
	global_load_dwordx4 v[204:207], v[140:141], off
	global_load_dwordx4 v[196:199], v[140:141], off offset:16
	global_load_dwordx4 v[188:191], v[140:141], off offset:528
	global_load_dwordx4 v[192:195], v[140:141], off offset:512
	v_lshl_add_u64 v[140:141], v[240:241], 2, v[234:235]
	v_mad_i64_i32 v[236:237], s[8:9], v65, v64, 0
	global_load_dwordx4 v[180:183], v[140:141], off offset:16
	global_load_dwordx4 v[184:187], v[140:141], off
	global_load_dwordx4 v[172:175], v[140:141], off offset:528
	global_load_dwordx4 v[176:179], v[140:141], off offset:512
	v_lshl_add_u64 v[140:141], v[238:239], 2, v[234:235]
	v_lshl_add_u64 v[144:145], v[236:237], 2, v[234:235]
	global_load_dwordx4 v[164:167], v[140:141], off offset:16
	global_load_dwordx4 v[168:171], v[140:141], off
	global_load_dwordx4 v[156:159], v[140:141], off offset:528
	global_load_dwordx4 v[160:163], v[140:141], off offset:512
	global_load_dwordx4 v[148:151], v[144:145], off offset:16
	global_load_dwordx4 v[152:155], v[144:145], off
	s_nop 0
	global_load_dwordx4 v[140:143], v[144:145], off offset:528
	s_nop 0
	global_load_dwordx4 v[144:147], v[144:145], off offset:512
	v_and_b32_e32 v64, 2, v67
	v_cmp_ne_u32_e64 s[10:11], 0, v64
	v_mad_i64_i32 v[202:203], s[18:19], v65, v228, v[230:231]
	v_ashrrev_i32_e32 v229, 31, v228
	s_mov_b64 s[8:9], -1
	v_lshl_add_u64 v[242:243], v[202:203], 2, v[138:139]
	s_and_b64 vcc, exec, s[10:11]
	s_waitcnt vmcnt(16)
	v_mov_b32_e32 v232, v66
	v_mov_b32_e32 v233, v66
	s_waitcnt vmcnt(15)
	v_pk_fma_f32 v[212:213], v[134:135], v[66:67], v[206:207] op_sel_hi:[1,0,1]
	v_pk_fma_f32 v[210:211], v[132:133], v[66:67], v[204:205] op_sel_hi:[1,0,1]
	s_waitcnt vmcnt(14)
	v_pk_fma_f32 v[208:209], v[128:129], v[232:233], v[196:197]
	s_waitcnt vmcnt(12)
	v_pk_fma_f32 v[204:205], v[124:125], v[232:233], v[192:193]
	v_pk_fma_f32 v[200:201], v[120:121], v[232:233], v[188:189]
	global_store_dwordx4 v[242:243], v[210:213], off
	s_cbranch_vccz .LBB0_1073
	v_mul_f32_e32 v64, v211, v211
	v_mul_f32_e32 v67, v213, v213
	v_fmac_f32_e32 v64, v210, v210
	v_fmac_f32_e32 v67, v212, v212
	v_add_f32_e32 v64, v64, v67
	v_mov_b32_e32 v67, v66
	v_cvt_pk_bf16_f32 v188, v210, v211
	v_cvt_pk_bf16_f32 v189, v212, v213
	v_lshl_add_u64 v[192:193], v[202:203], 1, v[68:69]
	v_pk_fma_f32 v[210:211], v[130:131], v[66:67], v[198:199]
	v_mov_b32_e32 v216, v188
	v_mov_b32_e32 v217, v189
	v_cvt_pk_bf16_f32 v188, v208, v209
	v_cvt_pk_bf16_f32 v189, v210, v211
	global_store_dwordx4 v[242:243], v[208:211], off offset:16
	v_mov_b32_e32 v218, v188
	v_mov_b32_e32 v219, v189
	global_store_dwordx4 v[192:193], v[216:219], off
	s_nop 0
	v_mul_f32_e32 v188, v209, v209
	v_mul_f32_e32 v189, v211, v211
	v_fmac_f32_e32 v188, v208, v208
	v_fmac_f32_e32 v189, v210, v210
	v_add_f32_e32 v188, v188, v189
	v_pk_fma_f32 v[206:207], v[126:127], v[66:67], v[194:195]
	v_add_f32_e32 v64, v64, v188
	v_cvt_pk_bf16_f32 v188, v204, v205
	v_cvt_pk_bf16_f32 v189, v206, v207
	global_store_dwordx4 v[242:243], v[204:207], off offset:512
	v_mov_b32_e32 v216, v188
	v_mov_b32_e32 v217, v189
	v_mul_f32_e32 v188, v205, v205
	v_mul_f32_e32 v189, v207, v207
	v_fmac_f32_e32 v188, v204, v204
	v_fmac_f32_e32 v189, v206, v206
	v_add_f32_e32 v188, v188, v189
	v_pk_fma_f32 v[202:203], v[122:123], v[66:67], v[190:191]
	v_add_f32_e32 v64, v188, v64
	v_mul_f32_e32 v67, v201, v201
	v_mul_f32_e32 v188, v203, v203
	v_fmac_f32_e32 v67, v200, v200
	v_fmac_f32_e32 v188, v202, v202
	v_add_f32_e32 v67, v67, v188
	v_add_f32_e32 v64, v67, v64
	ds_swizzle_b32 v67, v64 offset:swizzle(SWAP,16)
	v_cvt_pk_bf16_f32 v188, v200, v201
	v_cvt_pk_bf16_f32 v189, v202, v203
	global_store_dwordx4 v[242:243], v[200:203], off offset:528
	v_mov_b32_e32 v218, v188
	v_mov_b32_e32 v219, v189
	global_store_dwordx4 v[192:193], v[216:219], off offset:256
	s_nop 0
	s_waitcnt lgkmcnt(0)
	v_add_f32_e32 v64, v64, v67
	v_mov_b32_e32 v67, v64
	s_nop 1
	v_permlane32_swap_b32_e32 v64, v67
	s_and_saveexec_b64 s[8:9], s[4:5]
	s_cbranch_execz .LBB0_1072
	v_lshl_add_u64 v[188:189], v[228:229], 2, v[70:71]
	v_add_f32_e32 v64, v64, v67
	global_atomic_add_f32 v[188:189], v64, off

; __device__ __forceinline__ unsigned cvtpk(float lo, float hi) { f32x2 v = {lo, hi}; bf16x2_t b = __builtin_convertvector(v, bf16x2_t); return __builtin_bit_cast(unsigned, b); }
; #define SWZ_XOR(v, m) __uint_as_float((unsigned)__builtin_amdgcn_ds_swizzle((int)__float_as_uint(v), ((m) << 10) | 0x1f))
; __device__ __forceinline__ float sum32x(float v) { auto rr = __builtin_amdgcn_permlane32_swap(__float_as_uint(v), __float_as_uint(v), false, false); return __uint_as_float(rr[0]) + __uint_as_float(rr[1]); }
;     __device__ __forceinline__ void operator()(const pg8::f32x4 (&acc)[2][2][4][2], const pg8::Unit& u, int wr, int wc, int fr, int fq) const {
;     ...
;                 for (int m = 0; m < 4; ++m) {
;                     const size_t ro = (size_t)(rowb + 128 * ai + 16 * m) * ldc + colb;
;                     float ssr = 0.f;
; #pragma unroll
;                     for (int bj = 0; bj < 2; ++bj)
; #pragma unroll
;                         for (int n = 0; n < 2; ++n) {
;                             const size_t off = ro + 128 * bj + NS * n;
;                             const pg8::f32x4 v = pre[m][bj][n] + acc[ai][bj][m][n] * coef;
;                             *(pg8::f32x4*)(fout + off) = v;
;                             if (flags & 2) { u32x2 w; w.x = cvtpk(v[0], v[1]); w.y = cvtpk(v[2], v[3]); *(u32x2*)(o0 + off) = w; ssr += (v[0] * v[0] + v[1] * v[1]) + (v[2] * v[2] + v[3] * v[3]); }
;                         }
;                     if (flags & 2) { ssr += SWZ_XOR(ssr, 16); ssr = sum32x(ssr); if (fq == 0) atomicAdd((float*)o1 + (rowb + 128 * ai + 16 * m), ssr); }
;                 }
.LBB0_1075:
	v_lshl_add_u64 v[190:191], v[240:241], 0, v[230:231]
	v_mov_b32_e32 v67, v66
	v_cndmask_b32_e64 v64, 0, 1, s[10:11]
	s_waitcnt vmcnt(11)
	v_pk_fma_f32 v[196:197], v[118:119], v[66:67], v[186:187]
	v_pk_fma_f32 v[194:195], v[116:117], v[232:233], v[184:185]
	v_lshl_add_u64 v[198:199], v[190:191], 2, v[138:139]
	s_mov_b64 s[48:49], -1
	v_cmp_ne_u32_e64 s[8:9], 1, v64
	s_andn2_b64 vcc, exec, s[10:11]
	v_pk_fma_f32 v[192:193], v[108:109], v[232:233], v[180:181]
	s_waitcnt vmcnt(9)
	v_pk_fma_f32 v[188:189], v[112:113], v[232:233], v[176:177]
	v_pk_fma_f32 v[184:185], v[104:105], v[232:233], v[172:173]
	global_store_dwordx4 v[198:199], v[194:197], off
	s_cbranch_vccnz .LBB0_1079
	v_cvt_pk_bf16_f32 v172, v194, v195
	v_cvt_pk_bf16_f32 v173, v196, v197
	v_lshl_add_u64 v[176:177], v[190:191], 1, v[68:69]
	v_mov_b32_e32 v216, v172
	v_mov_b32_e32 v217, v173
	v_mul_f32_e32 v64, v195, v195
	v_mul_f32_e32 v172, v197, v197
	v_fmac_f32_e32 v64, v194, v194
	v_fmac_f32_e32 v172, v196, v196
	v_pk_fma_f32 v[194:195], v[110:111], v[66:67], v[182:183]
	v_add_f32_e32 v64, v64, v172
	v_cvt_pk_bf16_f32 v172, v192, v193
	v_cvt_pk_bf16_f32 v173, v194, v195
	global_store_dwordx4 v[198:199], v[192:195], off offset:16
	v_mov_b32_e32 v218, v172
	v_mov_b32_e32 v219, v173
	global_store_dwordx4 v[176:177], v[216:219], off
	s_nop 0
	v_mul_f32_e32 v172, v193, v193
	v_mul_f32_e32 v173, v195, v195
	v_fmac_f32_e32 v172, v192, v192
	v_fmac_f32_e32 v173, v194, v194
	v_add_f32_e32 v172, v172, v173
	v_pk_fma_f32 v[190:191], v[114:115], v[66:67], v[178:179]
	v_add_f32_e32 v64, v64, v172
	v_cvt_pk_bf16_f32 v172, v188, v189
	v_cvt_pk_bf16_f32 v173, v190, v191
	global_store_dwordx4 v[198:199], v[188:191], off offset:512
	v_mov_b32_e32 v216, v172
	v_mov_b32_e32 v217, v173
	v_mul_f32_e32 v172, v189, v189
	v_mul_f32_e32 v173, v191, v191
	v_fmac_f32_e32 v172, v188, v188
	v_fmac_f32_e32 v173, v190, v190
	v_add_f32_e32 v172, v172, v173
	v_pk_fma_f32 v[186:187], v[106:107], v[66:67], v[174:175]
	v_add_f32_e32 v64, v64, v172
	v_mul_f32_e32 v67, v185, v185
	v_mul_f32_e32 v172, v187, v187
	v_fmac_f32_e32 v67, v184, v184
	v_fmac_f32_e32 v172, v186, v186
	v_add_f32_e32 v67, v67, v172
	v_add_f32_e32 v64, v64, v67
	ds_swizzle_b32 v67, v64 offset:swizzle(SWAP,16)
	v_cvt_pk_bf16_f32 v172, v184, v185
	v_cvt_pk_bf16_f32 v173, v186, v187
	global_store_dwordx4 v[198:199], v[184:187], off offset:528
	v_mov_b32_e32 v218, v172
	v_mov_b32_e32 v219, v173
	global_store_dwordx4 v[176:177], v[216:219], off offset:256
	s_nop 0
	s_waitcnt lgkmcnt(0)
	v_add_f32_e32 v64, v64, v67
	v_mov_b32_e32 v67, v64
	s_nop 1
	v_permlane32_swap_b32_e32 v64, v67
	s_and_saveexec_b64 s[10:11], s[4:5]
	s_cbranch_execz .LBB0_1078
	v_lshl_add_u64 v[172:173], v[228:229], 2, v[70:71]
	v_add_f32_e32 v64, v64, v67
	global_atomic_add_f32 v[172:173], v64, off offset:64

; __device__ __forceinline__ unsigned cvtpk(float lo, float hi) { f32x2 v = {lo, hi}; bf16x2_t b = __builtin_convertvector(v, bf16x2_t); return __builtin_bit_cast(unsigned, b); }
; #define SWZ_XOR(v, m) __uint_as_float((unsigned)__builtin_amdgcn_ds_swizzle((int)__float_as_uint(v), ((m) << 10) | 0x1f))
; __device__ __forceinline__ float sum32x(float v) { auto rr = __builtin_amdgcn_permlane32_swap(__float_as_uint(v), __float_as_uint(v), false, false); return __uint_as_float(rr[0]) + __uint_as_float(rr[1]); }
;     __device__ __forceinline__ void operator()(const pg8::f32x4 (&acc)[2][2][4][2], const pg8::Unit& u, int wr, int wc, int fr, int fq) const {
;     ...
;                 for (int m = 0; m < 4; ++m) {
;                     const size_t ro = (size_t)(rowb + 128 * ai + 16 * m) * ldc + colb;
;                     float ssr = 0.f;
; #pragma unroll
;                     for (int bj = 0; bj < 2; ++bj)
; #pragma unroll
;                         for (int n = 0; n < 2; ++n) {
;                             const size_t off = ro + 128 * bj + NS * n;
;                             const pg8::f32x4 v = pre[m][bj][n] + acc[ai][bj][m][n] * coef;
;                             *(pg8::f32x4*)(fout + off) = v;
;                             if (flags & 2) { u32x2 w; w.x = cvtpk(v[0], v[1]); w.y = cvtpk(v[2], v[3]); *(u32x2*)(o0 + off) = w; ssr += (v[0] * v[0] + v[1] * v[1]) + (v[2] * v[2] + v[3] * v[3]); }
;                         }
;                     if (flags & 2) { ssr += SWZ_XOR(ssr, 16); ssr = sum32x(ssr); if (fq == 0) atomicAdd((float*)o1 + (rowb + 128 * ai + 16 * m), ssr); }
;                 }
.LBB0_1081:
	v_lshl_add_u64 v[174:175], v[238:239], 0, v[230:231]
	v_mov_b32_e32 v67, v66
	s_waitcnt vmcnt(8)
	v_pk_fma_f32 v[180:181], v[102:103], v[66:67], v[170:171]
	v_pk_fma_f32 v[178:179], v[100:101], v[232:233], v[168:169]
	v_lshl_add_u64 v[182:183], v[174:175], 2, v[138:139]
	s_mov_b64 s[10:11], -1
	s_and_b64 vcc, exec, s[8:9]
	v_pk_fma_f32 v[176:177], v[92:93], v[232:233], v[164:165]
	s_waitcnt vmcnt(6)
	v_pk_fma_f32 v[172:173], v[96:97], v[232:233], v[160:161]
	v_pk_fma_f32 v[168:169], v[88:89], v[232:233], v[156:157]
	global_store_dwordx4 v[182:183], v[178:181], off
	s_cbranch_vccnz .LBB0_1085
	v_cvt_pk_bf16_f32 v156, v178, v179
	v_cvt_pk_bf16_f32 v157, v180, v181
	v_lshl_add_u64 v[160:161], v[174:175], 1, v[68:69]
	v_mov_b32_e32 v216, v156
	v_mov_b32_e32 v217, v157
	v_mul_f32_e32 v64, v179, v179
	v_mul_f32_e32 v156, v181, v181
	v_fmac_f32_e32 v64, v178, v178
	v_fmac_f32_e32 v156, v180, v180
	v_pk_fma_f32 v[178:179], v[94:95], v[66:67], v[166:167]
	v_add_f32_e32 v64, v64, v156
	v_cvt_pk_bf16_f32 v156, v176, v177
	v_cvt_pk_bf16_f32 v157, v178, v179
	global_store_dwordx4 v[182:183], v[176:179], off offset:16
	v_mov_b32_e32 v218, v156
	v_mov_b32_e32 v219, v157
	global_store_dwordx4 v[160:161], v[216:219], off
	s_nop 0
	v_mul_f32_e32 v156, v177, v177
	v_mul_f32_e32 v157, v179, v179
	v_fmac_f32_e32 v156, v176, v176
	v_fmac_f32_e32 v157, v178, v178
	v_add_f32_e32 v156, v156, v157
	v_pk_fma_f32 v[174:175], v[98:99], v[66:67], v[162:163]
	v_add_f32_e32 v64, v64, v156
	v_cvt_pk_bf16_f32 v156, v172, v173
	v_cvt_pk_bf16_f32 v157, v174, v175
	global_store_dwordx4 v[182:183], v[172:175], off offset:512
	v_mov_b32_e32 v216, v156
	v_mov_b32_e32 v217, v157
	v_mul_f32_e32 v156, v173, v173
	v_mul_f32_e32 v157, v175, v175
	v_fmac_f32_e32 v156, v172, v172
	v_fmac_f32_e32 v157, v174, v174
	v_add_f32_e32 v156, v156, v157
	v_pk_fma_f32 v[170:171], v[90:91], v[66:67], v[158:159]
	v_add_f32_e32 v64, v64, v156
	v_mul_f32_e32 v67, v169, v169
	v_mul_f32_e32 v156, v171, v171
	v_fmac_f32_e32 v67, v168, v168
	v_fmac_f32_e32 v156, v170, v170
	v_add_f32_e32 v67, v67, v156
	v_add_f32_e32 v64, v64, v67
	ds_swizzle_b32 v67, v64 offset:swizzle(SWAP,16)
	v_cvt_pk_bf16_f32 v156, v168, v169
	v_cvt_pk_bf16_f32 v157, v170, v171
	global_store_dwordx4 v[182:183], v[168:171], off offset:528
	v_mov_b32_e32 v218, v156
	v_mov_b32_e32 v219, v157
	global_store_dwordx4 v[160:161], v[216:219], off offset:256
	s_nop 0
	s_waitcnt lgkmcnt(0)
	v_add_f32_e32 v64, v64, v67
	v_mov_b32_e32 v67, v64
	s_nop 1
	v_permlane32_swap_b32_e32 v64, v67
	s_and_saveexec_b64 s[10:11], s[4:5]
	s_cbranch_execz .LBB0_1084
	v_lshl_add_u64 v[156:157], v[228:229], 2, v[70:71]
	v_add_f32_e32 v64, v64, v67
	global_atomic_add_f32 v[156:157], v64, off offset:128

; __device__ __forceinline__ unsigned cvtpk(float lo, float hi) { f32x2 v = {lo, hi}; bf16x2_t b = __builtin_convertvector(v, bf16x2_t); return __builtin_bit_cast(unsigned, b); }
; #define SWZ_XOR(v, m) __uint_as_float((unsigned)__builtin_amdgcn_ds_swizzle((int)__float_as_uint(v), ((m) << 10) | 0x1f))
; __device__ __forceinline__ float sum32x(float v) { auto rr = __builtin_amdgcn_permlane32_swap(__float_as_uint(v), __float_as_uint(v), false, false); return __uint_as_float(rr[0]) + __uint_as_float(rr[1]); }
;     __device__ __forceinline__ void operator()(const pg8::f32x4 (&acc)[2][2][4][2], const pg8::Unit& u, int wr, int wc, int fr, int fq) const {
;     ...
;                 for (int m = 0; m < 4; ++m) {
;                     const size_t ro = (size_t)(rowb + 128 * ai + 16 * m) * ldc + colb;
;                     float ssr = 0.f;
; #pragma unroll
;                     for (int bj = 0; bj < 2; ++bj)
; #pragma unroll
;                         for (int n = 0; n < 2; ++n) {
;                             const size_t off = ro + 128 * bj + NS * n;
;                             const pg8::f32x4 v = pre[m][bj][n] + acc[ai][bj][m][n] * coef;
;                             *(pg8::f32x4*)(fout + off) = v;
;                             if (flags & 2) { u32x2 w; w.x = cvtpk(v[0], v[1]); w.y = cvtpk(v[2], v[3]); *(u32x2*)(o0 + off) = w; ssr += (v[0] * v[0] + v[1] * v[1]) + (v[2] * v[2] + v[3] * v[3]); }
;                         }
;                     if (flags & 2) { ssr += SWZ_XOR(ssr, 16); ssr = sum32x(ssr); if (fq == 0) atomicAdd((float*)o1 + (rowb + 128 * ai + 16 * m), ssr); }
;                 }
.LBB0_1087:
	v_lshl_add_u64 v[158:159], v[236:237], 0, v[230:231]
	v_mov_b32_e32 v67, v66
	s_waitcnt vmcnt(5)
	v_pk_fma_f32 v[164:165], v[86:87], v[66:67], v[154:155]
	v_pk_fma_f32 v[162:163], v[84:85], v[232:233], v[152:153]
	v_lshl_add_u64 v[166:167], v[158:159], 2, v[138:139]
	s_mov_b64 s[10:11], -1
	s_and_b64 vcc, exec, s[8:9]
	v_pk_fma_f32 v[160:161], v[76:77], v[232:233], v[148:149]
	s_waitcnt vmcnt(3)
	v_pk_fma_f32 v[156:157], v[80:81], v[232:233], v[144:145]
	v_pk_fma_f32 v[152:153], v[72:73], v[232:233], v[140:141]
	global_store_dwordx4 v[166:167], v[162:165], off
	s_cbranch_vccnz .LBB0_1091
	v_cvt_pk_bf16_f32 v140, v162, v163
	v_cvt_pk_bf16_f32 v141, v164, v165
	v_lshl_add_u64 v[144:145], v[158:159], 1, v[68:69]
	v_mov_b32_e32 v216, v140
	v_mov_b32_e32 v217, v141
	v_mul_f32_e32 v64, v163, v163
	v_mul_f32_e32 v140, v165, v165
	v_fmac_f32_e32 v64, v162, v162
	v_fmac_f32_e32 v140, v164, v164
	v_pk_fma_f32 v[162:163], v[78:79], v[66:67], v[150:151]
	v_add_f32_e32 v64, v64, v140
	v_cvt_pk_bf16_f32 v140, v160, v161
	v_cvt_pk_bf16_f32 v141, v162, v163
	global_store_dwordx4 v[166:167], v[160:163], off offset:16
	v_mov_b32_e32 v218, v140
	v_mov_b32_e32 v219, v141
	global_store_dwordx4 v[144:145], v[216:219], off
	s_nop 0
	v_mul_f32_e32 v140, v161, v161
	v_mul_f32_e32 v141, v163, v163
	v_fmac_f32_e32 v140, v160, v160
	v_fmac_f32_e32 v141, v162, v162
	v_add_f32_e32 v140, v140, v141
	v_pk_fma_f32 v[158:159], v[82:83], v[66:67], v[146:147]
	v_add_f32_e32 v64, v64, v140
	v_cvt_pk_bf16_f32 v140, v156, v157
	v_cvt_pk_bf16_f32 v141, v158, v159
	global_store_dwordx4 v[166:167], v[156:159], off offset:512
	v_mov_b32_e32 v216, v140
	v_mov_b32_e32 v217, v141
	v_mul_f32_e32 v140, v157, v157
	v_mul_f32_e32 v141, v159, v159
	v_fmac_f32_e32 v140, v156, v156
	v_fmac_f32_e32 v141, v158, v158
	v_add_f32_e32 v140, v140, v141
	v_pk_fma_f32 v[154:155], v[74:75], v[66:67], v[142:143]
	v_add_f32_e32 v64, v64, v140
	v_mul_f32_e32 v67, v153, v153
	v_mul_f32_e32 v140, v155, v155
	v_fmac_f32_e32 v67, v152, v152
	v_fmac_f32_e32 v140, v154, v154
	v_add_f32_e32 v67, v67, v140
	v_add_f32_e32 v64, v64, v67
	ds_swizzle_b32 v67, v64 offset:swizzle(SWAP,16)
	v_cvt_pk_bf16_f32 v140, v152, v153
	v_cvt_pk_bf16_f32 v141, v154, v155
	global_store_dwordx4 v[166:167], v[152:155], off offset:528
	v_mov_b32_e32 v218, v140
	v_mov_b32_e32 v219, v141
	global_store_dwordx4 v[144:145], v[216:219], off offset:256
	s_nop 0
	s_waitcnt lgkmcnt(0)
	v_add_f32_e32 v64, v64, v67
	v_mov_b32_e32 v67, v64
	s_nop 1
	v_permlane32_swap_b32_e32 v64, v67
	s_and_saveexec_b64 s[10:11], s[4:5]
	s_cbranch_execz .LBB0_1090
	v_lshl_add_u64 v[140:141], v[228:229], 2, v[70:71]
	v_add_f32_e32 v64, v64, v67
	global_atomic_add_f32 v[140:141], v64, off offset:192

; __device__ __forceinline__ unsigned cvtpk(float lo, float hi) { f32x2 v = {lo, hi}; bf16x2_t b = __builtin_convertvector(v, bf16x2_t); return __builtin_bit_cast(unsigned, b); }
; #define SWZ_XOR(v, m) __uint_as_float((unsigned)__builtin_amdgcn_ds_swizzle((int)__float_as_uint(v), ((m) << 10) | 0x1f))
; __device__ __forceinline__ float sum32x(float v) { auto rr = __builtin_amdgcn_permlane32_swap(__float_as_uint(v), __float_as_uint(v), false, false); return __uint_as_float(rr[0]) + __uint_as_float(rr[1]); }
;     __device__ __forceinline__ void operator()(const pg8::f32x4 (&acc)[2][2][4][2], const pg8::Unit& u, int wr, int wc, int fr, int fq) const {
;     ...
;             for (int ai = 0; ai < 2; ++ai) {
;                 pg8::f32x4 pre[4][2][2];
; #pragma unroll
;                 for (int m = 0; m < 4; ++m) {
;                     const size_t ro = (size_t)(rowb + 128 * ai + 16 * m) * ldc + colb;
; #pragma unroll
;                     for (int bj = 0; bj < 2; ++bj)
; #pragma unroll
;                         for (int n = 0; n < 2; ++n) pre[m][bj][n] = *(const pg8::f32x4*)(fin + ro + 128 * bj + NS * n);
;                 }
; #pragma unroll
;                 for (int m = 0; m < 4; ++m) {
;                     const size_t ro = (size_t)(rowb + 128 * ai + 16 * m) * ldc + colb;
;                     float ssr = 0.f;
; #pragma unroll
;                     for (int bj = 0; bj < 2; ++bj)
; #pragma unroll
;                         for (int n = 0; n < 2; ++n) {
;                             const size_t off = ro + 128 * bj + NS * n;
;                             const pg8::f32x4 v = pre[m][bj][n] + acc[ai][bj][m][n] * coef;
;                             *(pg8::f32x4*)(fout + off) = v;
;                             if (flags & 2) { u32x2 w; w.x = cvtpk(v[0], v[1]); w.y = cvtpk(v[2], v[3]); *(u32x2*)(o0 + off) = w; ssr += (v[0] * v[0] + v[1] * v[1]) + (v[2] * v[2] + v[3] * v[3]); }
;                         }
;                     if (flags & 2) { ssr += SWZ_XOR(ssr, 16); ssr = sum32x(ssr); if (fq == 0) atomicAdd((float*)o1 + (rowb + 128 * ai + 16 * m), ssr); }
;                 }
.LBB0_1093:
	v_add_u32_e32 v64, 0x80, v228
	v_add_u32_e32 v67, 0x90, v228
	v_mad_i64_i32 v[140:141], s[10:11], v65, v64, 0
	v_mad_i64_i32 v[240:241], s[10:11], v65, v67, 0
	v_add_u32_e32 v67, 0xa0, v228
	v_lshl_add_u64 v[140:141], v[140:141], 2, v[234:235]
	v_mad_i64_i32 v[238:239], s[10:11], v65, v67, 0
	v_add_u32_e32 v67, 0xb0, v228
	global_load_dwordx4 v[204:207], v[140:141], off
	global_load_dwordx4 v[196:199], v[140:141], off offset:16
	global_load_dwordx4 v[188:191], v[140:141], off offset:528
	global_load_dwordx4 v[192:195], v[140:141], off offset:512
	v_lshl_add_u64 v[140:141], v[240:241], 2, v[234:235]
	v_mad_i64_i32 v[236:237], s[10:11], v65, v67, 0
	global_load_dwordx4 v[180:183], v[140:141], off offset:16
	global_load_dwordx4 v[184:187], v[140:141], off
	global_load_dwordx4 v[172:175], v[140:141], off offset:528
	global_load_dwordx4 v[176:179], v[140:141], off offset:512
	v_lshl_add_u64 v[140:141], v[238:239], 2, v[234:235]
	v_lshl_add_u64 v[144:145], v[236:237], 2, v[234:235]
	global_load_dwordx4 v[164:167], v[140:141], off offset:16
	global_load_dwordx4 v[168:171], v[140:141], off
	global_load_dwordx4 v[156:159], v[140:141], off offset:528
	global_load_dwordx4 v[160:163], v[140:141], off offset:512
	global_load_dwordx4 v[148:151], v[144:145], off offset:16
	global_load_dwordx4 v[152:155], v[144:145], off
	s_nop 0
	global_load_dwordx4 v[140:143], v[144:145], off offset:528
	s_nop 0
	global_load_dwordx4 v[144:147], v[144:145], off offset:512
	v_mad_i64_i32 v[202:203], s[10:11], v65, v64, v[230:231]
	v_mov_b32_e32 v67, v66
	v_lshl_add_u64 v[234:235], v[202:203], 2, v[138:139]
	s_mov_b64 s[10:11], -1
	s_and_b64 vcc, exec, s[8:9]
	s_waitcnt vmcnt(15)
	v_pk_fma_f32 v[212:213], v[62:63], v[66:67], v[206:207]
	v_pk_fma_f32 v[210:211], v[60:61], v[232:233], v[204:205]
	s_waitcnt vmcnt(14)
	v_pk_fma_f32 v[208:209], v[52:53], v[232:233], v[196:197]
	s_waitcnt vmcnt(12)
	v_pk_fma_f32 v[204:205], v[56:57], v[232:233], v[192:193]
	v_pk_fma_f32 v[200:201], v[48:49], v[232:233], v[188:189]
	global_store_dwordx4 v[234:235], v[210:213], off
	s_cbranch_vccnz .LBB0_1097
	v_cvt_pk_bf16_f32 v188, v210, v211
	v_cvt_pk_bf16_f32 v189, v212, v213
	v_lshl_add_u64 v[192:193], v[202:203], 1, v[68:69]
	v_mov_b32_e32 v216, v188
	v_mov_b32_e32 v217, v189
	v_mul_f32_e32 v64, v211, v211
	v_mul_f32_e32 v188, v213, v213
	v_fmac_f32_e32 v64, v210, v210
	v_fmac_f32_e32 v188, v212, v212
	v_pk_fma_f32 v[210:211], v[54:55], v[66:67], v[198:199]
	v_add_f32_e32 v64, v64, v188
	v_cvt_pk_bf16_f32 v188, v208, v209
	v_cvt_pk_bf16_f32 v189, v210, v211
	global_store_dwordx4 v[234:235], v[208:211], off offset:16
	v_mov_b32_e32 v218, v188
	v_mov_b32_e32 v219, v189
	global_store_dwordx4 v[192:193], v[216:219], off
	s_nop 0
	v_mul_f32_e32 v188, v209, v209
	v_mul_f32_e32 v189, v211, v211
	v_fmac_f32_e32 v188, v208, v208
	v_fmac_f32_e32 v189, v210, v210
	v_add_f32_e32 v188, v188, v189
	v_pk_fma_f32 v[206:207], v[58:59], v[66:67], v[194:195]
	v_add_f32_e32 v64, v64, v188
	v_cvt_pk_bf16_f32 v188, v204, v205
	v_cvt_pk_bf16_f32 v189, v206, v207
	global_store_dwordx4 v[234:235], v[204:207], off offset:512
	v_mov_b32_e32 v216, v188
	v_mov_b32_e32 v217, v189
	v_mul_f32_e32 v188, v205, v205
	v_mul_f32_e32 v189, v207, v207
	v_fmac_f32_e32 v188, v204, v204
	v_fmac_f32_e32 v189, v206, v206
	v_add_f32_e32 v188, v188, v189
	v_pk_fma_f32 v[202:203], v[50:51], v[66:67], v[190:191]
	v_add_f32_e32 v64, v64, v188
	v_mul_f32_e32 v67, v201, v201
	v_mul_f32_e32 v188, v203, v203
	v_fmac_f32_e32 v67, v200, v200
	v_fmac_f32_e32 v188, v202, v202
	v_add_f32_e32 v67, v67, v188
	v_add_f32_e32 v64, v64, v67
	ds_swizzle_b32 v67, v64 offset:swizzle(SWAP,16)
	v_cvt_pk_bf16_f32 v188, v200, v201
	v_cvt_pk_bf16_f32 v189, v202, v203
	global_store_dwordx4 v[234:235], v[200:203], off offset:528
	v_mov_b32_e32 v218, v188
	v_mov_b32_e32 v219, v189
	global_store_dwordx4 v[192:193], v[216:219], off offset:256
	s_nop 0
	s_waitcnt lgkmcnt(0)
	v_add_f32_e32 v64, v64, v67
	v_mov_b32_e32 v67, v64
	s_nop 1
	v_permlane32_swap_b32_e32 v64, v67
	s_and_saveexec_b64 s[10:11], s[4:5]
	s_cbranch_execz .LBB0_1096
	v_lshl_add_u64 v[188:189], v[228:229], 2, v[70:71]
	v_add_f32_e32 v64, v64, v67
	global_atomic_add_f32 v[188:189], v64, off offset:512

; __device__ __forceinline__ unsigned cvtpk(float lo, float hi) { f32x2 v = {lo, hi}; bf16x2_t b = __builtin_convertvector(v, bf16x2_t); return __builtin_bit_cast(unsigned, b); }
; #define SWZ_XOR(v, m) __uint_as_float((unsigned)__builtin_amdgcn_ds_swizzle((int)__float_as_uint(v), ((m) << 10) | 0x1f))
; __device__ __forceinline__ float sum32x(float v) { auto rr = __builtin_amdgcn_permlane32_swap(__float_as_uint(v), __float_as_uint(v), false, false); return __uint_as_float(rr[0]) + __uint_as_float(rr[1]); }
;     __device__ __forceinline__ void operator()(const pg8::f32x4 (&acc)[2][2][4][2], const pg8::Unit& u, int wr, int wc, int fr, int fq) const {
;     ...
;                 for (int m = 0; m < 4; ++m) {
;                     const size_t ro = (size_t)(rowb + 128 * ai + 16 * m) * ldc + colb;
;                     float ssr = 0.f;
; #pragma unroll
;                     for (int bj = 0; bj < 2; ++bj)
; #pragma unroll
;                         for (int n = 0; n < 2; ++n) {
;                             const size_t off = ro + 128 * bj + NS * n;
;                             const pg8::f32x4 v = pre[m][bj][n] + acc[ai][bj][m][n] * coef;
;                             *(pg8::f32x4*)(fout + off) = v;
;                             if (flags & 2) { u32x2 w; w.x = cvtpk(v[0], v[1]); w.y = cvtpk(v[2], v[3]); *(u32x2*)(o0 + off) = w; ssr += (v[0] * v[0] + v[1] * v[1]) + (v[2] * v[2] + v[3] * v[3]); }
;                         }
;                     if (flags & 2) { ssr += SWZ_XOR(ssr, 16); ssr = sum32x(ssr); if (fq == 0) atomicAdd((float*)o1 + (rowb + 128 * ai + 16 * m), ssr); }
;                 }
.LBB0_1099:
	v_lshl_add_u64 v[190:191], v[240:241], 0, v[230:231]
	v_mov_b32_e32 v67, v66
	s_waitcnt vmcnt(11)
	v_pk_fma_f32 v[196:197], v[46:47], v[66:67], v[186:187]
	v_pk_fma_f32 v[194:195], v[44:45], v[232:233], v[184:185]
	v_lshl_add_u64 v[198:199], v[190:191], 2, v[138:139]
	s_mov_b64 s[10:11], -1
	s_and_b64 vcc, exec, s[8:9]
	v_pk_fma_f32 v[192:193], v[36:37], v[232:233], v[180:181]
	s_waitcnt vmcnt(9)
	v_pk_fma_f32 v[188:189], v[40:41], v[232:233], v[176:177]
	v_pk_fma_f32 v[184:185], v[32:33], v[232:233], v[172:173]
	global_store_dwordx4 v[198:199], v[194:197], off
	s_cbranch_vccnz .LBB0_1103
	v_cvt_pk_bf16_f32 v172, v194, v195
	v_cvt_pk_bf16_f32 v173, v196, v197
	v_lshl_add_u64 v[176:177], v[190:191], 1, v[68:69]
	v_mov_b32_e32 v216, v172
	v_mov_b32_e32 v217, v173
	v_mul_f32_e32 v64, v195, v195
	v_mul_f32_e32 v172, v197, v197
	v_fmac_f32_e32 v64, v194, v194
	v_fmac_f32_e32 v172, v196, v196
	v_pk_fma_f32 v[194:195], v[38:39], v[66:67], v[182:183]
	v_add_f32_e32 v64, v64, v172
	v_cvt_pk_bf16_f32 v172, v192, v193
	v_cvt_pk_bf16_f32 v173, v194, v195
	global_store_dwordx4 v[198:199], v[192:195], off offset:16
	v_mov_b32_e32 v218, v172
	v_mov_b32_e32 v219, v173
	global_store_dwordx4 v[176:177], v[216:219], off
	s_nop 0
	v_mul_f32_e32 v172, v193, v193
	v_mul_f32_e32 v173, v195, v195
	v_fmac_f32_e32 v172, v192, v192
	v_fmac_f32_e32 v173, v194, v194
	v_add_f32_e32 v172, v172, v173
	v_pk_fma_f32 v[190:191], v[42:43], v[66:67], v[178:179]
	v_add_f32_e32 v64, v64, v172
	v_cvt_pk_bf16_f32 v172, v188, v189
	v_cvt_pk_bf16_f32 v173, v190, v191
	global_store_dwordx4 v[198:199], v[188:191], off offset:512
	v_mov_b32_e32 v216, v172
	v_mov_b32_e32 v217, v173
	v_mul_f32_e32 v172, v189, v189
	v_mul_f32_e32 v173, v191, v191
	v_fmac_f32_e32 v172, v188, v188
	v_fmac_f32_e32 v173, v190, v190
	v_add_f32_e32 v172, v172, v173
	v_pk_fma_f32 v[186:187], v[34:35], v[66:67], v[174:175]
	v_add_f32_e32 v64, v64, v172
	v_mul_f32_e32 v67, v185, v185
	v_mul_f32_e32 v172, v187, v187
	v_fmac_f32_e32 v67, v184, v184
	v_fmac_f32_e32 v172, v186, v186
	v_add_f32_e32 v67, v67, v172
	v_add_f32_e32 v64, v64, v67
	ds_swizzle_b32 v67, v64 offset:swizzle(SWAP,16)
	v_cvt_pk_bf16_f32 v172, v184, v185
	v_cvt_pk_bf16_f32 v173, v186, v187
	global_store_dwordx4 v[198:199], v[184:187], off offset:528
	v_mov_b32_e32 v218, v172
	v_mov_b32_e32 v219, v173
	global_store_dwordx4 v[176:177], v[216:219], off offset:256
	s_nop 0
	s_waitcnt lgkmcnt(0)
	v_add_f32_e32 v64, v64, v67
	v_mov_b32_e32 v67, v64
	s_nop 1
	v_permlane32_swap_b32_e32 v64, v67
	s_and_saveexec_b64 s[10:11], s[4:5]
	s_cbranch_execz .LBB0_1102
	v_lshl_add_u64 v[172:173], v[228:229], 2, v[70:71]
	v_add_f32_e32 v64, v64, v67
	global_atomic_add_f32 v[172:173], v64, off offset:576

; __device__ __forceinline__ unsigned cvtpk(float lo, float hi) { f32x2 v = {lo, hi}; bf16x2_t b = __builtin_convertvector(v, bf16x2_t); return __builtin_bit_cast(unsigned, b); }
; #define SWZ_XOR(v, m) __uint_as_float((unsigned)__builtin_amdgcn_ds_swizzle((int)__float_as_uint(v), ((m) << 10) | 0x1f))
; __device__ __forceinline__ float sum32x(float v) { auto rr = __builtin_amdgcn_permlane32_swap(__float_as_uint(v), __float_as_uint(v), false, false); return __uint_as_float(rr[0]) + __uint_as_float(rr[1]); }
;     __device__ __forceinline__ void operator()(const pg8::f32x4 (&acc)[2][2][4][2], const pg8::Unit& u, int wr, int wc, int fr, int fq) const {
;     ...
;                 for (int m = 0; m < 4; ++m) {
;                     const size_t ro = (size_t)(rowb + 128 * ai + 16 * m) * ldc + colb;
;                     float ssr = 0.f;
; #pragma unroll
;                     for (int bj = 0; bj < 2; ++bj)
; #pragma unroll
;                         for (int n = 0; n < 2; ++n) {
;                             const size_t off = ro + 128 * bj + NS * n;
;                             const pg8::f32x4 v = pre[m][bj][n] + acc[ai][bj][m][n] * coef;
;                             *(pg8::f32x4*)(fout + off) = v;
;                             if (flags & 2) { u32x2 w; w.x = cvtpk(v[0], v[1]); w.y = cvtpk(v[2], v[3]); *(u32x2*)(o0 + off) = w; ssr += (v[0] * v[0] + v[1] * v[1]) + (v[2] * v[2] + v[3] * v[3]); }
;                         }
;                     if (flags & 2) { ssr += SWZ_XOR(ssr, 16); ssr = sum32x(ssr); if (fq == 0) atomicAdd((float*)o1 + (rowb + 128 * ai + 16 * m), ssr); }
;                 }
.LBB0_1105:
	v_lshl_add_u64 v[174:175], v[238:239], 0, v[230:231]
	v_mov_b32_e32 v67, v66
	s_waitcnt vmcnt(8)
	v_pk_fma_f32 v[180:181], v[30:31], v[66:67], v[170:171]
	v_pk_fma_f32 v[178:179], v[28:29], v[232:233], v[168:169]
	v_lshl_add_u64 v[182:183], v[174:175], 2, v[138:139]
	s_mov_b64 s[10:11], -1
	s_and_b64 vcc, exec, s[8:9]
	v_pk_fma_f32 v[176:177], v[20:21], v[232:233], v[164:165]
	s_waitcnt vmcnt(6)
	v_pk_fma_f32 v[172:173], v[24:25], v[232:233], v[160:161]
	v_pk_fma_f32 v[168:169], v[16:17], v[232:233], v[156:157]
	global_store_dwordx4 v[182:183], v[178:181], off
	s_cbranch_vccnz .LBB0_1109
	v_cvt_pk_bf16_f32 v156, v178, v179
	v_cvt_pk_bf16_f32 v157, v180, v181
	v_lshl_add_u64 v[160:161], v[174:175], 1, v[68:69]
	v_mov_b32_e32 v216, v156
	v_mov_b32_e32 v217, v157
	v_mul_f32_e32 v64, v179, v179
	v_mul_f32_e32 v156, v181, v181
	v_fmac_f32_e32 v64, v178, v178
	v_fmac_f32_e32 v156, v180, v180
	v_pk_fma_f32 v[178:179], v[22:23], v[66:67], v[166:167]
	v_add_f32_e32 v64, v64, v156
	v_cvt_pk_bf16_f32 v156, v176, v177
	v_cvt_pk_bf16_f32 v157, v178, v179
	global_store_dwordx4 v[182:183], v[176:179], off offset:16
	v_mov_b32_e32 v218, v156
	v_mov_b32_e32 v219, v157
	global_store_dwordx4 v[160:161], v[216:219], off
	s_nop 0
	v_mul_f32_e32 v156, v177, v177
	v_mul_f32_e32 v157, v179, v179
	v_fmac_f32_e32 v156, v176, v176
	v_fmac_f32_e32 v157, v178, v178
	v_add_f32_e32 v156, v156, v157
	v_pk_fma_f32 v[174:175], v[26:27], v[66:67], v[162:163]
	v_add_f32_e32 v64, v64, v156
	v_cvt_pk_bf16_f32 v156, v172, v173
	v_cvt_pk_bf16_f32 v157, v174, v175
	global_store_dwordx4 v[182:183], v[172:175], off offset:512
	v_mov_b32_e32 v216, v156
	v_mov_b32_e32 v217, v157
	v_mul_f32_e32 v156, v173, v173
	v_mul_f32_e32 v157, v175, v175
	v_fmac_f32_e32 v156, v172, v172
	v_fmac_f32_e32 v157, v174, v174
	v_add_f32_e32 v156, v156, v157
	v_pk_fma_f32 v[170:171], v[18:19], v[66:67], v[158:159]
	v_add_f32_e32 v64, v64, v156
	v_mul_f32_e32 v67, v169, v169
	v_mul_f32_e32 v156, v171, v171
	v_fmac_f32_e32 v67, v168, v168
	v_fmac_f32_e32 v156, v170, v170
	v_add_f32_e32 v67, v67, v156
	v_add_f32_e32 v64, v64, v67
	ds_swizzle_b32 v67, v64 offset:swizzle(SWAP,16)
	v_cvt_pk_bf16_f32 v156, v168, v169
	v_cvt_pk_bf16_f32 v157, v170, v171
	global_store_dwordx4 v[182:183], v[168:171], off offset:528
	v_mov_b32_e32 v218, v156
	v_mov_b32_e32 v219, v157
	global_store_dwordx4 v[160:161], v[216:219], off offset:256
	s_nop 0
	s_waitcnt lgkmcnt(0)
	v_add_f32_e32 v64, v64, v67
	v_mov_b32_e32 v67, v64
	s_nop 1
	v_permlane32_swap_b32_e32 v64, v67
	s_and_saveexec_b64 s[10:11], s[4:5]
	s_cbranch_execz .LBB0_1108
	v_lshl_add_u64 v[156:157], v[228:229], 2, v[70:71]
	v_add_f32_e32 v64, v64, v67
	global_atomic_add_f32 v[156:157], v64, off offset:640

; __device__ __forceinline__ unsigned cvtpk(float lo, float hi) { f32x2 v = {lo, hi}; bf16x2_t b = __builtin_convertvector(v, bf16x2_t); return __builtin_bit_cast(unsigned, b); }
; #define SWZ_XOR(v, m) __uint_as_float((unsigned)__builtin_amdgcn_ds_swizzle((int)__float_as_uint(v), ((m) << 10) | 0x1f))
; __device__ __forceinline__ float sum32x(float v) { auto rr = __builtin_amdgcn_permlane32_swap(__float_as_uint(v), __float_as_uint(v), false, false); return __uint_as_float(rr[0]) + __uint_as_float(rr[1]); }
;     __device__ __forceinline__ void operator()(const pg8::f32x4 (&acc)[2][2][4][2], const pg8::Unit& u, int wr, int wc, int fr, int fq) const {
;     ...
;                 for (int m = 0; m < 4; ++m) {
;                     const size_t ro = (size_t)(rowb + 128 * ai + 16 * m) * ldc + colb;
;                     float ssr = 0.f;
; #pragma unroll
;                     for (int bj = 0; bj < 2; ++bj)
; #pragma unroll
;                         for (int n = 0; n < 2; ++n) {
;                             const size_t off = ro + 128 * bj + NS * n;
;                             const pg8::f32x4 v = pre[m][bj][n] + acc[ai][bj][m][n] * coef;
;                             *(pg8::f32x4*)(fout + off) = v;
;                             if (flags & 2) { u32x2 w; w.x = cvtpk(v[0], v[1]); w.y = cvtpk(v[2], v[3]); *(u32x2*)(o0 + off) = w; ssr += (v[0] * v[0] + v[1] * v[1]) + (v[2] * v[2] + v[3] * v[3]); }
;                         }
;                     if (flags & 2) { ssr += SWZ_XOR(ssr, 16); ssr = sum32x(ssr); if (fq == 0) atomicAdd((float*)o1 + (rowb + 128 * ai + 16 * m), ssr); }
;                 }
.LBB0_1111:
	v_lshl_add_u64 v[164:165], v[236:237], 0, v[230:231]
	v_mov_b32_e32 v67, v66
	s_waitcnt vmcnt(5)
	v_pk_fma_f32 v[160:161], v[14:15], v[66:67], v[154:155]
	v_pk_fma_f32 v[158:159], v[12:13], v[232:233], v[152:153]
	v_lshl_add_u64 v[162:163], v[164:165], 2, v[138:139]
	s_mov_b64 s[10:11], -1
	s_and_b64 vcc, exec, s[8:9]
	v_pk_fma_f32 v[156:157], v[4:5], v[232:233], v[148:149]
	s_waitcnt vmcnt(3)
	v_pk_fma_f32 v[152:153], v[8:9], v[232:233], v[144:145]
	v_pk_fma_f32 v[138:139], v[0:1], v[232:233], v[140:141]
	global_store_dwordx4 v[162:163], v[158:161], off
	s_cbranch_vccnz .LBB0_1115
	v_cvt_pk_bf16_f32 v140, v158, v159
	v_cvt_pk_bf16_f32 v141, v160, v161
	v_lshl_add_u64 v[144:145], v[164:165], 1, v[68:69]
	v_mov_b32_e32 v216, v140
	v_mov_b32_e32 v217, v141
	v_mul_f32_e32 v64, v159, v159
	v_mul_f32_e32 v140, v161, v161
	v_fmac_f32_e32 v64, v158, v158
	v_fmac_f32_e32 v140, v160, v160
	v_pk_fma_f32 v[158:159], v[6:7], v[66:67], v[150:151]
	v_add_f32_e32 v64, v64, v140
	v_cvt_pk_bf16_f32 v140, v156, v157
	v_cvt_pk_bf16_f32 v141, v158, v159
	global_store_dwordx4 v[162:163], v[156:159], off offset:16
	v_mov_b32_e32 v218, v140
	v_mov_b32_e32 v219, v141
	global_store_dwordx4 v[144:145], v[216:219], off
	s_nop 0
	v_mul_f32_e32 v140, v157, v157
	v_mul_f32_e32 v141, v159, v159
	v_fmac_f32_e32 v140, v156, v156
	v_fmac_f32_e32 v141, v158, v158
	v_add_f32_e32 v140, v140, v141
	v_pk_fma_f32 v[154:155], v[10:11], v[66:67], v[146:147]
	v_add_f32_e32 v64, v64, v140
	v_cvt_pk_bf16_f32 v140, v152, v153
	v_cvt_pk_bf16_f32 v141, v154, v155
	global_store_dwordx4 v[162:163], v[152:155], off offset:512
	v_mov_b32_e32 v216, v140
	v_mov_b32_e32 v217, v141
	v_mul_f32_e32 v140, v153, v153
	v_mul_f32_e32 v141, v155, v155
	v_fmac_f32_e32 v140, v152, v152
	v_fmac_f32_e32 v141, v154, v154
	v_add_f32_e32 v140, v140, v141
	v_add_f32_e32 v64, v64, v140
	v_pk_fma_f32 v[140:141], v[2:3], v[66:67], v[142:143]
	v_mul_f32_e32 v67, v139, v139
	v_mul_f32_e32 v148, v141, v141
	v_fmac_f32_e32 v67, v138, v138
	v_fmac_f32_e32 v148, v140, v140
	v_add_f32_e32 v67, v67, v148
	v_add_f32_e32 v64, v64, v67
	ds_swizzle_b32 v67, v64 offset:swizzle(SWAP,16)
	v_cvt_pk_bf16_f32 v148, v138, v139
	v_cvt_pk_bf16_f32 v149, v140, v141
	global_store_dwordx4 v[162:163], v[138:141], off offset:528
	v_mov_b32_e32 v218, v148
	v_mov_b32_e32 v219, v149
	global_store_dwordx4 v[144:145], v[216:219], off offset:256
	s_nop 0
	s_waitcnt lgkmcnt(0)
	v_add_f32_e32 v64, v64, v67
	v_mov_b32_e32 v67, v64
	s_nop 1
	v_permlane32_swap_b32_e32 v64, v67
	s_and_saveexec_b64 s[8:9], s[4:5]
	s_cbranch_execz .LBB0_1114
	v_lshl_add_u64 v[70:71], v[228:229], 2, v[70:71]
	v_add_f32_e32 v64, v64, v67
	global_atomic_add_f32 v[70:71], v64, off offset:704

; template <class Epi, class Sched, bool ALIGN_EPI = false, bool SP2 = false>
; __device__ __forceinline__ void gemm_phase(PG8_LAS unsigned char* lds, const Gemm g, const Sched& S, const Epi& E, const int wave0) {
;     ...
;         if constexpr (!Epi::AFTER_DRAIN) { E(acc, cur, wr, wc, fr, fq); S.done(cur); }
;         if (!has_next) break;
.LBB0_1117:
.LBB0_1118:
	v_mov_b32_e32 v216, v221
	v_mov_b32_e32 v218, v223
	s_mov_b64 s[8:9], 0

; __device__ __forceinline__ unsigned cvtpk(float lo, float hi) { f32x2 v = {lo, hi}; bf16x2_t b = __builtin_convertvector(v, bf16x2_t); return __builtin_bit_cast(unsigned, b); }
; #define SWZ_XOR(v, m) __uint_as_float((unsigned)__builtin_amdgcn_ds_swizzle((int)__float_as_uint(v), ((m) << 10) | 0x1f))
; __device__ __forceinline__ float sum32x(float v) { auto rr = __builtin_amdgcn_permlane32_swap(__float_as_uint(v), __float_as_uint(v), false, false); return __uint_as_float(rr[0]) + __uint_as_float(rr[1]); }
;     __device__ __forceinline__ void operator()(const pg8::f32x4 (&acc)[2][2][4][2], const pg8::Unit& u, int wr, int wc, int fr, int fq) const {
;     ...
;                 for (int m = 0; m < 4; ++m) {
;                     const size_t ro = (size_t)(rowb + 128 * ai + 16 * m) * ldc + colb;
;                     float ssr = 0.f;
; #pragma unroll
;                     for (int bj = 0; bj < 2; ++bj)
; #pragma unroll
;                         for (int n = 0; n < 2; ++n) {
;                             const size_t off = ro + 128 * bj + NS * n;
;                             const pg8::f32x4 v = pre[m][bj][n] + acc[ai][bj][m][n] * coef;
;                             *(pg8::f32x4*)(fout + off) = v;
;                             if (flags & 2) { u32x2 w; w.x = cvtpk(v[0], v[1]); w.y = cvtpk(v[2], v[3]); *(u32x2*)(o0 + off) = w; ssr += (v[0] * v[0] + v[1] * v[1]) + (v[2] * v[2] + v[3] * v[3]); }
;                         }
;                     if (flags & 2) { ssr += SWZ_XOR(ssr, 16); ssr = sum32x(ssr); if (fq == 0) atomicAdd((float*)o1 + (rowb + 128 * ai + 16 * m), ssr); }
;                 }
.LBB0_1191:
	v_lshl_add_u64 v[190:191], v[240:241], 0, v[230:231]
	v_mov_b32_e32 v67, v66
	v_cndmask_b32_e64 v64, 0, 1, s[10:11]
	s_waitcnt vmcnt(11)
	v_pk_fma_f32 v[196:197], v[118:119], v[66:67], v[186:187]
	v_pk_fma_f32 v[194:195], v[116:117], v[232:233], v[184:185]
	v_lshl_add_u64 v[198:199], v[190:191], 2, v[138:139]
	s_mov_b64 s[56:57], -1
	v_cmp_ne_u32_e64 s[8:9], 1, v64
	s_andn2_b64 vcc, exec, s[10:11]
	v_pk_fma_f32 v[192:193], v[108:109], v[232:233], v[180:181]
	s_waitcnt vmcnt(9)
	v_pk_fma_f32 v[188:189], v[112:113], v[232:233], v[176:177]
	v_pk_fma_f32 v[184:185], v[104:105], v[232:233], v[172:173]
	global_store_dwordx4 v[198:199], v[194:197], off
	s_cbranch_vccnz .LBB0_1195
	v_cvt_pk_bf16_f32 v172, v194, v195
	v_cvt_pk_bf16_f32 v173, v196, v197
	v_lshl_add_u64 v[176:177], v[190:191], 1, v[68:69]
	v_mov_b32_e32 v216, v172
	v_mov_b32_e32 v217, v173
	v_mul_f32_e32 v64, v195, v195
	v_mul_f32_e32 v172, v197, v197
	v_fmac_f32_e32 v64, v194, v194
	v_fmac_f32_e32 v172, v196, v196
	v_pk_fma_f32 v[194:195], v[110:111], v[66:67], v[182:183]
	v_add_f32_e32 v64, v64, v172
	v_cvt_pk_bf16_f32 v172, v192, v193
	v_cvt_pk_bf16_f32 v173, v194, v195
	global_store_dwordx4 v[198:199], v[192:195], off offset:16
	v_mov_b32_e32 v218, v172
	v_mov_b32_e32 v219, v173
	global_store_dwordx4 v[176:177], v[216:219], off
	s_nop 0
	v_mul_f32_e32 v172, v193, v193
	v_mul_f32_e32 v173, v195, v195
	v_fmac_f32_e32 v172, v192, v192
	v_fmac_f32_e32 v173, v194, v194
	v_add_f32_e32 v172, v172, v173
	v_pk_fma_f32 v[190:191], v[114:115], v[66:67], v[178:179]
	v_add_f32_e32 v64, v64, v172
	v_cvt_pk_bf16_f32 v172, v188, v189
	v_cvt_pk_bf16_f32 v173, v190, v191
	global_store_dwordx4 v[198:199], v[188:191], off offset:512
	v_mov_b32_e32 v216, v172
	v_mov_b32_e32 v217, v173
	v_mul_f32_e32 v172, v189, v189
	v_mul_f32_e32 v173, v191, v191
	v_fmac_f32_e32 v172, v188, v188
	v_fmac_f32_e32 v173, v190, v190
	v_add_f32_e32 v172, v172, v173
	v_pk_fma_f32 v[186:187], v[106:107], v[66:67], v[174:175]
	v_add_f32_e32 v64, v64, v172
	v_mul_f32_e32 v67, v185, v185
	v_mul_f32_e32 v172, v187, v187
	v_fmac_f32_e32 v67, v184, v184
	v_fmac_f32_e32 v172, v186, v186
	v_add_f32_e32 v67, v67, v172
	v_add_f32_e32 v64, v64, v67
	ds_swizzle_b32 v67, v64 offset:swizzle(SWAP,16)
	v_cvt_pk_bf16_f32 v172, v184, v185
	v_cvt_pk_bf16_f32 v173, v186, v187
	global_store_dwordx4 v[198:199], v[184:187], off offset:528
	v_mov_b32_e32 v218, v172
	v_mov_b32_e32 v219, v173
	global_store_dwordx4 v[176:177], v[216:219], off offset:256
	s_nop 0
	s_waitcnt lgkmcnt(0)
	v_add_f32_e32 v64, v64, v67
	v_mov_b32_e32 v67, v64
	s_nop 1
	v_permlane32_swap_b32_e32 v64, v67
	s_and_saveexec_b64 s[10:11], s[4:5]
	s_cbranch_execz .LBB0_1194
	v_lshl_add_u64 v[172:173], v[228:229], 2, v[70:71]
	v_add_f32_e32 v64, v64, v67
	global_atomic_add_f32 v[172:173], v64, off offset:64
